# gate|up phase: the two wave halves keep their one-phase stagger through the epilogue (no re-alignment barriers per unit)
# baseline (speedup 1.0000x reference)
.LBB11_2567:
	s_add_u32 s0, s26, 0xfffc0080
	s_addc_u32 s1, s27, -1
	s_add_i32 s48, 0, 0x10000
	s_cmp_eq_u32 s68, 12
	s_cselect_b32 s31, s9, s1
	s_cselect_b32 s30, s47, s0
	s_cselect_b32 s29, s56, s59
	s_cselect_b32 s28, s57, s58
	s_add_i32 s49, 0, 0x14000
	v_add_u32_e32 v158, s48, v142
	v_add_u32_e32 v174, s49, v142
	ds_read_b128 v[146:149], v158
	ds_read_b128 v[150:153], v158 offset:1024
	ds_read_b128 v[154:157], v158 offset:2048
	ds_read_b128 v[158:161], v158 offset:3072
	ds_read_b128 v[162:165], v174
	ds_read_b128 v[166:169], v174 offset:1024
	ds_read_b128 v[170:173], v174 offset:2048
	ds_read_b128 v[174:177], v174 offset:3072
	v_lshl_add_u64 v[182:183], s[26:27], 0, v[136:137]
	s_add_i32 m0, s36, 0xc000
	ds_read_b128 v[178:181], v145
	ds_read_b128 v[190:193], v145 offset:1024
	ds_read_b128 v[194:197], v145 offset:2048
	ds_read_b128 v[214:217], v145 offset:3072
	ds_read_b128 v[218:221], v145 offset:4096
	ds_read_b128 v[222:225], v145 offset:5120
	ds_read_b128 v[226:229], v145 offset:6144
	ds_read_b128 v[230:233], v145 offset:7168
	global_load_lds_dwordx4 v[182:183], off
	v_lshl_add_u64 v[182:183], s[26:27], 0, v[138:139]
	s_add_i32 m0, s36, 0xe000
	s_nop 0
	global_load_lds_dwordx4 v[182:183], off
	s_waitcnt vmcnt(8)
	s_waitcnt lgkmcnt(0)
	s_barrier
	s_setprio 1
	v_mfma_f32_16x16x32_bf16 v[126:129], v[146:149], v[178:181], v[126:129]
	v_mfma_f32_16x16x32_bf16 v[118:121], v[154:157], v[178:181], v[118:121]
	v_mfma_f32_16x16x32_bf16 v[110:113], v[146:149], v[194:197], v[110:113]
	v_mfma_f32_16x16x32_bf16 v[102:105], v[154:157], v[194:197], v[102:105]
	v_mfma_f32_16x16x32_bf16 v[94:97], v[146:149], v[218:221], v[94:97]
	v_mfma_f32_16x16x32_bf16 v[86:89], v[154:157], v[218:221], v[86:89]
	v_mfma_f32_16x16x32_bf16 v[78:81], v[146:149], v[226:229], v[78:81]
	v_mfma_f32_16x16x32_bf16 v[70:73], v[154:157], v[226:229], v[70:73]
	v_mfma_f32_16x16x32_bf16 v[126:129], v[150:153], v[190:193], v[126:129]
	v_mfma_f32_16x16x32_bf16 v[118:121], v[158:161], v[190:193], v[118:121]
	v_mfma_f32_16x16x32_bf16 v[110:113], v[150:153], v[214:217], v[110:113]
	v_mfma_f32_16x16x32_bf16 v[102:105], v[158:161], v[214:217], v[102:105]
	v_mfma_f32_16x16x32_bf16 v[94:97], v[150:153], v[222:225], v[94:97]
	v_mfma_f32_16x16x32_bf16 v[86:89], v[158:161], v[222:225], v[86:89]
	v_mfma_f32_16x16x32_bf16 v[78:81], v[150:153], v[230:233], v[78:81]
	v_mfma_f32_16x16x32_bf16 v[70:73], v[158:161], v[230:233], v[70:73]
	v_mfma_f32_16x16x32_bf16 v[122:125], v[162:165], v[178:181], v[122:125]
	v_mfma_f32_16x16x32_bf16 v[114:117], v[170:173], v[178:181], v[114:117]
	v_mfma_f32_16x16x32_bf16 v[106:109], v[162:165], v[194:197], v[106:109]
	v_mfma_f32_16x16x32_bf16 v[98:101], v[170:173], v[194:197], v[98:101]
	v_mfma_f32_16x16x32_bf16 v[90:93], v[162:165], v[218:221], v[90:93]
	v_mfma_f32_16x16x32_bf16 v[82:85], v[170:173], v[218:221], v[82:85]
	v_mfma_f32_16x16x32_bf16 v[74:77], v[162:165], v[226:229], v[74:77]
	v_mfma_f32_16x16x32_bf16 v[66:69], v[170:173], v[226:229], v[66:69]
	v_mfma_f32_16x16x32_bf16 v[122:125], v[166:169], v[190:193], v[122:125]
	v_mfma_f32_16x16x32_bf16 v[114:117], v[174:177], v[190:193], v[114:117]
	v_mfma_f32_16x16x32_bf16 v[106:109], v[166:169], v[214:217], v[106:109]
	v_mfma_f32_16x16x32_bf16 v[98:101], v[174:177], v[214:217], v[98:101]
	v_mfma_f32_16x16x32_bf16 v[90:93], v[166:169], v[222:225], v[90:93]
	v_mfma_f32_16x16x32_bf16 v[82:85], v[174:177], v[222:225], v[82:85]
	v_mfma_f32_16x16x32_bf16 v[74:77], v[166:169], v[230:233], v[74:77]
	v_mfma_f32_16x16x32_bf16 v[66:69], v[174:177], v[230:233], v[66:69]
	s_setprio 0
	s_barrier
	s_add_i32 s0, s48, s35
	v_lshl_add_u64 v[182:183], s[28:29], 0, v[0:1]
	s_mov_b32 m0, s0
	ds_read_b128 v[178:181], v145 offset:16384
	ds_read_b128 v[190:193], v145 offset:17408
	ds_read_b128 v[194:197], v145 offset:18432
	ds_read_b128 v[214:217], v145 offset:19456
	ds_read_b128 v[218:221], v145 offset:20480
	ds_read_b128 v[222:225], v145 offset:21504
	ds_read_b128 v[226:229], v145 offset:22528
	ds_read_b128 v[230:233], v145 offset:23552
	global_load_lds_dwordx4 v[182:183], off
	s_add_i32 m0, s0, 0x2000
	s_add_u32 s0, s28, 0x40000
	v_lshl_add_u64 v[234:235], s[28:29], 0, v[134:135]
	s_addc_u32 s1, s29, 0
	s_add_i32 s48, s49, s35
	global_load_lds_dwordx4 v[234:235], off
	v_lshl_add_u64 v[236:237], s[0:1], 0, v[0:1]
	s_mov_b32 m0, s48
	v_lshl_add_u64 v[238:239], s[30:31], 0, v[132:133]
	global_load_lds_dwordx4 v[236:237], off
	v_lshl_add_u64 v[236:237], s[0:1], 0, v[134:135]
	s_add_i32 m0, s48, 0x2000
	s_nop 0
	global_load_lds_dwordx4 v[236:237], off
	v_lshl_add_u64 v[236:237], s[30:31], 0, v[130:131]
	s_mov_b32 m0, s36
	s_nop 0
	global_load_lds_dwordx4 v[236:237], off
	s_mov_b32 m0, s37
	s_nop 0
	global_load_lds_dwordx4 v[238:239], off
	s_waitcnt vmcnt(8)
	s_waitcnt lgkmcnt(0)
	s_barrier
	s_setprio 1
	v_mfma_f32_16x16x32_bf16 v[62:65], v[146:149], v[178:181], v[62:65]
	v_mfma_f32_16x16x32_bf16 v[54:57], v[154:157], v[178:181], v[54:57]
	v_mfma_f32_16x16x32_bf16 v[46:49], v[146:149], v[194:197], v[46:49]
	v_mfma_f32_16x16x32_bf16 v[38:41], v[154:157], v[194:197], v[38:41]
	v_mfma_f32_16x16x32_bf16 v[30:33], v[146:149], v[218:221], v[30:33]
	v_mfma_f32_16x16x32_bf16 v[22:25], v[154:157], v[218:221], v[22:25]
	v_mfma_f32_16x16x32_bf16 v[14:17], v[146:149], v[226:229], v[14:17]
	v_mfma_f32_16x16x32_bf16 v[6:9], v[154:157], v[226:229], v[6:9]
	v_mfma_f32_16x16x32_bf16 v[62:65], v[150:153], v[190:193], v[62:65]
	v_mfma_f32_16x16x32_bf16 v[54:57], v[158:161], v[190:193], v[54:57]
	v_mfma_f32_16x16x32_bf16 v[46:49], v[150:153], v[214:217], v[46:49]
	v_mfma_f32_16x16x32_bf16 v[38:41], v[158:161], v[214:217], v[38:41]
	v_mfma_f32_16x16x32_bf16 v[30:33], v[150:153], v[222:225], v[30:33]
	v_mfma_f32_16x16x32_bf16 v[22:25], v[158:161], v[222:225], v[22:25]
	v_mfma_f32_16x16x32_bf16 v[14:17], v[150:153], v[230:233], v[14:17]
	v_mfma_f32_16x16x32_bf16 v[6:9], v[158:161], v[230:233], v[6:9]
	v_mfma_f32_16x16x32_bf16 v[58:61], v[162:165], v[178:181], v[58:61]
	v_mfma_f32_16x16x32_bf16 v[50:53], v[170:173], v[178:181], v[50:53]
	v_mfma_f32_16x16x32_bf16 v[42:45], v[162:165], v[194:197], v[42:45]
	v_mfma_f32_16x16x32_bf16 v[34:37], v[170:173], v[194:197], v[34:37]
	v_mfma_f32_16x16x32_bf16 v[26:29], v[162:165], v[218:221], v[26:29]
	v_mfma_f32_16x16x32_bf16 v[18:21], v[170:173], v[218:221], v[18:21]
	v_mfma_f32_16x16x32_bf16 v[10:13], v[162:165], v[226:229], v[10:13]
	v_mfma_f32_16x16x32_bf16 v[2:5], v[170:173], v[226:229], v[2:5]
	v_mfma_f32_16x16x32_bf16 v[58:61], v[166:169], v[190:193], v[58:61]
	v_mfma_f32_16x16x32_bf16 v[50:53], v[174:177], v[190:193], v[50:53]
	v_mfma_f32_16x16x32_bf16 v[42:45], v[166:169], v[214:217], v[42:45]
	v_mfma_f32_16x16x32_bf16 v[34:37], v[174:177], v[214:217], v[34:37]
	v_mfma_f32_16x16x32_bf16 v[26:29], v[166:169], v[222:225], v[26:29]
	v_mfma_f32_16x16x32_bf16 v[18:21], v[174:177], v[222:225], v[18:21]
	v_mfma_f32_16x16x32_bf16 v[10:13], v[166:169], v[230:233], v[10:13]
	v_mfma_f32_16x16x32_bf16 v[2:5], v[174:177], v[230:233], v[2:5]
	s_setprio 0
	s_barrier
	s_add_i32 s48, 0, 0x18000
	s_add_i32 s49, 0, 0x1c000
	v_add_u32_e32 v158, s48, v142
	v_add_u32_e32 v174, s49, v142
	ds_read_b128 v[146:149], v158
	ds_read_b128 v[150:153], v158 offset:1024
	ds_read_b128 v[154:157], v158 offset:2048
	ds_read_b128 v[158:161], v158 offset:3072
	ds_read_b128 v[162:165], v174
	ds_read_b128 v[166:169], v174 offset:1024
	ds_read_b128 v[170:173], v174 offset:2048
	ds_read_b128 v[174:177], v174 offset:3072
	s_add_u32 s0, s30, 0x40000
	s_addc_u32 s1, s31, 0
	s_mov_b32 m0, s38
	v_lshl_add_u64 v[240:241], s[0:1], 0, v[130:131]
	ds_read_b128 v[178:181], v145 offset:32768
	ds_read_b128 v[190:193], v145 offset:33792
	ds_read_b128 v[194:197], v145 offset:34816
	ds_read_b128 v[214:217], v145 offset:35840
	ds_read_b128 v[218:221], v145 offset:36864
	ds_read_b128 v[222:225], v145 offset:37888
	ds_read_b128 v[226:229], v145 offset:38912
	ds_read_b128 v[230:233], v145 offset:39936
	global_load_lds_dwordx4 v[240:241], off
	v_lshl_add_u64 v[240:241], s[0:1], 0, v[132:133]
	s_mov_b32 m0, s39
	s_nop 0
	global_load_lds_dwordx4 v[240:241], off
	s_waitcnt vmcnt(8)
	s_waitcnt lgkmcnt(0)
	s_barrier
	s_setprio 1
	v_mfma_f32_16x16x32_bf16 v[126:129], v[146:149], v[178:181], v[126:129]
	v_mfma_f32_16x16x32_bf16 v[118:121], v[154:157], v[178:181], v[118:121]
	v_mfma_f32_16x16x32_bf16 v[110:113], v[146:149], v[194:197], v[110:113]
	v_mfma_f32_16x16x32_bf16 v[102:105], v[154:157], v[194:197], v[102:105]
	v_mfma_f32_16x16x32_bf16 v[94:97], v[146:149], v[218:221], v[94:97]
	v_mfma_f32_16x16x32_bf16 v[86:89], v[154:157], v[218:221], v[86:89]
	v_mfma_f32_16x16x32_bf16 v[78:81], v[146:149], v[226:229], v[78:81]
	v_mfma_f32_16x16x32_bf16 v[70:73], v[154:157], v[226:229], v[70:73]
	v_mfma_f32_16x16x32_bf16 v[126:129], v[150:153], v[190:193], v[126:129]
	v_mfma_f32_16x16x32_bf16 v[118:121], v[158:161], v[190:193], v[118:121]
	v_mfma_f32_16x16x32_bf16 v[110:113], v[150:153], v[214:217], v[110:113]
	v_mfma_f32_16x16x32_bf16 v[102:105], v[158:161], v[214:217], v[102:105]
	v_mfma_f32_16x16x32_bf16 v[94:97], v[150:153], v[222:225], v[94:97]
	v_mfma_f32_16x16x32_bf16 v[86:89], v[158:161], v[222:225], v[86:89]
	v_mfma_f32_16x16x32_bf16 v[78:81], v[150:153], v[230:233], v[78:81]
	v_mfma_f32_16x16x32_bf16 v[70:73], v[158:161], v[230:233], v[70:73]
	v_mfma_f32_16x16x32_bf16 v[122:125], v[162:165], v[178:181], v[122:125]
	v_mfma_f32_16x16x32_bf16 v[114:117], v[170:173], v[178:181], v[114:117]
	v_mfma_f32_16x16x32_bf16 v[106:109], v[162:165], v[194:197], v[106:109]
	v_mfma_f32_16x16x32_bf16 v[98:101], v[170:173], v[194:197], v[98:101]
	v_mfma_f32_16x16x32_bf16 v[90:93], v[162:165], v[218:221], v[90:93]
	v_mfma_f32_16x16x32_bf16 v[82:85], v[170:173], v[218:221], v[82:85]
	v_mfma_f32_16x16x32_bf16 v[74:77], v[162:165], v[226:229], v[74:77]
	v_mfma_f32_16x16x32_bf16 v[66:69], v[170:173], v[226:229], v[66:69]
	v_mfma_f32_16x16x32_bf16 v[122:125], v[166:169], v[190:193], v[122:125]
	v_mfma_f32_16x16x32_bf16 v[114:117], v[174:177], v[190:193], v[114:117]
	v_mfma_f32_16x16x32_bf16 v[106:109], v[166:169], v[214:217], v[106:109]
	v_mfma_f32_16x16x32_bf16 v[98:101], v[174:177], v[214:217], v[98:101]
	v_mfma_f32_16x16x32_bf16 v[90:93], v[166:169], v[222:225], v[90:93]
	v_mfma_f32_16x16x32_bf16 v[82:85], v[174:177], v[222:225], v[82:85]
	v_mfma_f32_16x16x32_bf16 v[74:77], v[166:169], v[230:233], v[74:77]
	v_mfma_f32_16x16x32_bf16 v[66:69], v[174:177], v[230:233], v[66:69]
	s_setprio 0
	s_barrier
	s_add_i32 s0, s48, s35
	v_lshl_add_u64 v[182:183], v[182:183], 0, s[96:97]
	s_mov_b32 m0, s0
	ds_read_b128 v[178:181], v145 offset:49152
	ds_read_b128 v[190:193], v145 offset:50176
	ds_read_b128 v[194:197], v145 offset:51200
	ds_read_b128 v[214:217], v145 offset:52224
	ds_read_b128 v[218:221], v145 offset:53248
	ds_read_b128 v[222:225], v145 offset:54272
	ds_read_b128 v[226:229], v145 offset:55296
	ds_read_b128 v[230:233], v145 offset:56320
	global_load_lds_dwordx4 v[182:183], off
	s_add_i32 m0, s0, 0x2000
	s_add_u32 s0, s28, 0x40080
	v_lshl_add_u64 v[182:183], v[234:235], 0, s[96:97]
	s_addc_u32 s1, s29, 0
	s_add_i32 s28, s49, s35
	global_load_lds_dwordx4 v[182:183], off
	v_lshl_add_u64 v[182:183], s[0:1], 0, v[0:1]
	s_mov_b32 m0, s28
	s_nop 0
	global_load_lds_dwordx4 v[182:183], off
	v_lshl_add_u64 v[182:183], s[0:1], 0, v[134:135]
	s_add_i32 m0, s28, 0x2000
	s_nop 0
	global_load_lds_dwordx4 v[182:183], off
	v_lshl_add_u64 v[182:183], v[236:237], 0, s[96:97]
	s_mov_b32 m0, s40
	s_nop 0
	global_load_lds_dwordx4 v[182:183], off
	v_lshl_add_u64 v[182:183], v[238:239], 0, s[96:97]
	s_mov_b32 m0, s41
	s_nop 0
	global_load_lds_dwordx4 v[182:183], off
	s_waitcnt vmcnt(8)
	s_waitcnt lgkmcnt(0)
	s_barrier
	s_setprio 1
	v_mfma_f32_16x16x32_bf16 v[62:65], v[146:149], v[178:181], v[62:65]
	v_mfma_f32_16x16x32_bf16 v[54:57], v[154:157], v[178:181], v[54:57]
	v_mfma_f32_16x16x32_bf16 v[46:49], v[146:149], v[194:197], v[46:49]
	v_mfma_f32_16x16x32_bf16 v[38:41], v[154:157], v[194:197], v[38:41]
	v_mfma_f32_16x16x32_bf16 v[30:33], v[146:149], v[218:221], v[30:33]
	v_mfma_f32_16x16x32_bf16 v[22:25], v[154:157], v[218:221], v[22:25]
	v_mfma_f32_16x16x32_bf16 v[14:17], v[146:149], v[226:229], v[14:17]
	v_mfma_f32_16x16x32_bf16 v[6:9], v[154:157], v[226:229], v[6:9]
	v_mfma_f32_16x16x32_bf16 v[62:65], v[150:153], v[190:193], v[62:65]
	v_mfma_f32_16x16x32_bf16 v[54:57], v[158:161], v[190:193], v[54:57]
	v_mfma_f32_16x16x32_bf16 v[46:49], v[150:153], v[214:217], v[46:49]
	v_mfma_f32_16x16x32_bf16 v[38:41], v[158:161], v[214:217], v[38:41]
	v_mfma_f32_16x16x32_bf16 v[30:33], v[150:153], v[222:225], v[30:33]
	v_mfma_f32_16x16x32_bf16 v[22:25], v[158:161], v[222:225], v[22:25]
	v_mfma_f32_16x16x32_bf16 v[14:17], v[150:153], v[230:233], v[14:17]
	v_mfma_f32_16x16x32_bf16 v[6:9], v[158:161], v[230:233], v[6:9]
	v_mfma_f32_16x16x32_bf16 v[58:61], v[162:165], v[178:181], v[58:61]
	v_mfma_f32_16x16x32_bf16 v[50:53], v[170:173], v[178:181], v[50:53]
	v_mfma_f32_16x16x32_bf16 v[42:45], v[162:165], v[194:197], v[42:45]
	v_mfma_f32_16x16x32_bf16 v[34:37], v[170:173], v[194:197], v[34:37]
	v_mfma_f32_16x16x32_bf16 v[26:29], v[162:165], v[218:221], v[26:29]
	v_mfma_f32_16x16x32_bf16 v[18:21], v[170:173], v[218:221], v[18:21]
	v_mfma_f32_16x16x32_bf16 v[10:13], v[162:165], v[226:229], v[10:13]
	v_mfma_f32_16x16x32_bf16 v[2:5], v[170:173], v[226:229], v[2:5]
	v_mfma_f32_16x16x32_bf16 v[58:61], v[166:169], v[190:193], v[58:61]
	v_mfma_f32_16x16x32_bf16 v[50:53], v[174:177], v[190:193], v[50:53]
	v_mfma_f32_16x16x32_bf16 v[42:45], v[166:169], v[214:217], v[42:45]
	v_mfma_f32_16x16x32_bf16 v[34:37], v[174:177], v[214:217], v[34:37]
	v_mfma_f32_16x16x32_bf16 v[26:29], v[166:169], v[222:225], v[26:29]
	v_mfma_f32_16x16x32_bf16 v[18:21], v[174:177], v[222:225], v[18:21]
	v_mfma_f32_16x16x32_bf16 v[10:13], v[166:169], v[230:233], v[10:13]
	v_mfma_f32_16x16x32_bf16 v[2:5], v[174:177], v[230:233], v[2:5]
	s_setprio 0
	s_barrier
	s_add_i32 s68, s68, 2
	s_add_u32 s26, s26, 0x100
	s_addc_u32 s27, s27, 0
	s_add_u32 s58, s58, 0x100
	s_addc_u32 s59, s59, 0
	s_cmp_gt_u32 s68, 13
	s_cbranch_scc0 .LBB11_2567
	s_and_b64 vcc, exec, s[20:21]
	s_cbranch_vccz .LBB11_2570
	s_nop 0

.LBB11_2574:
	s_or_b64 exec, exec, s[26:27]
	s_andn2_b64 vcc, exec, s[12:13]
	s_mov_b64 s[12:13], -1
	s_cbranch_vccnz .LBB11_2563
	s_andn2_b64 vcc, exec, s[18:19]
	s_cbranch_vccnz .LBB11_2562
	s_nop 0
	s_branch .LBB11_2562
.LBB11_2577:
	s_waitcnt vmcnt(0)
	s_and_b64 vcc, exec, s[20:21]
	s_cbranch_vccz .Lswg_tail
	s_barrier
.Lswg_tail:
	s_barrier
.LBB11_2578:
	s_getreg_b32 s100, hwreg(HW_REG_XCC_ID, 0, 4)
	s_and_b32 s100, s100, 15
	s_lshl_b32 s100, s100, 8
	v_readlane_b32 s101, v248, 6
	s_nop 3
	s_add_u32 s100, s101, s100
	v_readlane_b32 s101, v248, 7
	s_nop 3
	s_addc_u32 s101, s101, 0
	s_nop 4
	global_load_dword v251, v208, s[100:101] offset:1024 sc1
	s_getreg_b32 s0, hwreg(HW_REG_XCC_ID, 0, 4)
	s_waitcnt vmcnt(0)
	s_waitcnt vmcnt(0) lgkmcnt(0)
	s_barrier
	s_mov_b64 s[6:7], exec
	v_readlane_b32 s8, v248, 2
	v_readlane_b32 s9, v248, 3
	s_and_b64 s[8:9], s[6:7], s[8:9]
	s_xor_b64 s[10:11], s[8:9], s[6:7]
	s_mov_b64 exec, s[8:9]
	s_getreg_b32 s1, hwreg(HW_REG_XCC_ID, 0, 4)
	s_andn2_saveexec_b64 s[10:11], s[10:11]
	s_cbranch_execz .LBB11_2666
	v_readlane_b32 s1, v242, 31
	s_waitcnt vmcnt(0) expcnt(0) lgkmcnt(0)
	s_and_b32 s6, s0, 15
	v_mov_b32_e32 v0, s1
	ds_read_b32 v2, v0
	v_readlane_b32 s1, v242, 32
	s_waitcnt lgkmcnt(0)
	v_cmp_ne_u32_e32 vcc, 0, v2
	v_mov_b32_e32 v0, s1
	ds_read_b32 v0, v0
	s_cbranch_vccnz .LBB11_2596
	s_mov_b32 s0, 1
	s_branch .LBB11_2584
